# P2 and P7 epilogue stores sc0 sc1 nt
# baseline (speedup 1.0000x reference)
; __device__ __forceinline__ unsigned cvt_pk_bf16(float lo, float hi) { unsigned r; asm volatile("v_cvt_pk_bf16_f32 %0, %1, %2" : "=v"(r) : "v"(lo), "v"(hi)); return r; }
; __device__ __forceinline__ float sigm(float x) { return __builtin_amdgcn_rcpf(1.0f + __builtin_amdgcn_exp2f(-1.4426950408889634f * x)); }
;     __device__ __forceinline__ void operator()(const f32x4 (&acc)[2][2][4][2], const Unit& u, int wr, int wc, int fr, int fq) const {
;         const int row0 = u.pm * BM + wr * 64 + fr, col0 = u.pn * 128 + wc * 32 + 8 * fq;
; #pragma unroll
;         for (int ai = 0; ai < 2; ++ai)
; #pragma unroll
;             for (int m = 0; m < 4; ++m) { bf16_t* rowp = out + (size_t)(row0 + ai * HALF + m * 16) * 2816 + col0;
;                 const f32x4 g0 = acc[ai][0][m][0], g1 = acc[ai][0][m][1], u0 = acc[ai][1][m][0], u1 = acc[ai][1][m][1];
;                 u32x4 w;
;                 w.x = cvt_pk_bf16(g0[0] * sigm(g0[0]) * u0[0], g0[1] * sigm(g0[1]) * u0[1]);
;                 w.y = cvt_pk_bf16(g0[2] * sigm(g0[2]) * u0[2], g0[3] * sigm(g0[3]) * u0[3]);
;                 w.z = cvt_pk_bf16(g1[0] * sigm(g1[0]) * u1[0], g1[1] * sigm(g1[1]) * u1[1]);
;                 w.w = cvt_pk_bf16(g1[2] * sigm(g1[2]) * u1[2], g1[3] * sigm(g1[3]) * u1[3]);
;                 __builtin_nontemporal_store(w, (u32x4*)rowp); }
.LBB0_608:
	s_add_u32 s100, s52, 0x40080
	s_addc_u32 s101, s13, 0
	v_lshl_add_u64 v[216:217], s[100:101], 0, v[136:137]
	s_add_i32 m0, s29, 0xc000
	v_lshl_add_u64 v[218:219], s[100:101], 0, v[138:139]
	global_load_lds_dwordx4 v[216:217], off
	s_add_i32 m0, s29, 0xe000
	s_nop 0
	global_load_lds_dwordx4 v[218:219], off
	v_mul_f32_e32 v155, 0xbfb8aa3b, v124
	v_exp_f32_e32 v155, v155
	v_mul_f32_e32 v158, 0xbfb8aa3b, v125
	v_exp_f32_e32 v158, v158
	v_lshl_or_b32 v146, s51, 7, v150
	v_add_f32_e32 v155, 1.0, v155
	v_rcp_f32_e32 v155, v155
	v_add_f32_e32 v158, 1.0, v158
	v_rcp_f32_e32 v158, v158
	v_lshl_add_u32 v154, s36, 8, v148
	v_mul_f32_e32 v124, v124, v155
	v_mul_f32_e32 v116, v124, v116
	v_mul_f32_e32 v124, v125, v158
	v_mul_f32_e32 v125, 0xbfb8aa3b, v126
	v_exp_f32_e32 v125, v125
	v_mul_f32_e32 v155, 0xbfb8aa3b, v127
	v_exp_f32_e32 v155, v155
	v_mul_f32_e32 v117, v124, v117
	v_add_f32_e32 v124, 1.0, v125
	v_rcp_f32_e32 v124, v124
	v_add_f32_e32 v125, 1.0, v155
	v_rcp_f32_e32 v125, v125
	v_cvt_pk_bf16_f32 v116, v116, v117
	v_mul_f32_e32 v117, v126, v124
	v_mul_f32_e32 v124, 0xbfb8aa3b, v120
	v_exp_f32_e32 v124, v124
	v_mul_f32_e32 v117, v117, v118
	v_mul_f32_e32 v118, v127, v125
	v_mul_f32_e32 v125, 0xbfb8aa3b, v121
	v_exp_f32_e32 v125, v125
	v_mul_f32_e32 v118, v118, v119
	v_add_f32_e32 v119, 1.0, v124
	v_rcp_f32_e32 v119, v119
	v_add_f32_e32 v124, 1.0, v125
	v_rcp_f32_e32 v124, v124
	v_cvt_pk_bf16_f32 v117, v117, v118
	v_mul_f32_e32 v118, v120, v119
	v_mul_f32_e32 v119, 0xbfb8aa3b, v122
	v_exp_f32_e32 v119, v119
	v_mul_f32_e32 v120, 0xbfb8aa3b, v123
	v_exp_f32_e32 v120, v120
	v_mul_f32_e32 v112, v118, v112
	v_mul_f32_e32 v118, v121, v124
	v_mul_f32_e32 v113, v118, v113
	v_add_f32_e32 v118, 1.0, v119
	v_rcp_f32_e32 v119, v118
	v_add_f32_e32 v118, 1.0, v120
	v_rcp_f32_e32 v120, v118
	v_cvt_pk_bf16_f32 v118, v112, v113
	v_mul_f32_e32 v112, v122, v119
	v_mul_f32_e32 v112, v112, v114
	v_mul_f32_e32 v113, v123, v120
	v_mul_f32_e32 v113, v113, v115
	v_cvt_pk_bf16_f32 v119, v112, v113
	v_mul_f32_e32 v113, 0xbfb8aa3b, v108
	v_exp_f32_e32 v114, v113
	v_mul_f32_e32 v113, 0xbfb8aa3b, v109
	v_exp_f32_e32 v115, v113
	v_ashrrev_i32_e32 v147, 31, v146
	v_add_f32_e32 v114, 1.0, v114
	v_rcp_f32_e32 v114, v114
	v_add_f32_e32 v115, 1.0, v115
	v_rcp_f32_e32 v115, v115
	v_mov_b64_e32 v[144:145], s[18:19]
	v_mul_f32_e32 v108, v108, v114
	v_mul_f32_e32 v100, v108, v100
	v_mul_f32_e32 v108, v109, v115
	v_mul_f32_e32 v109, 0xbfb8aa3b, v110
	v_exp_f32_e32 v109, v109
	v_mul_f32_e32 v114, 0xbfb8aa3b, v111
	v_exp_f32_e32 v114, v114
	v_mul_f32_e32 v101, v108, v101
	v_add_f32_e32 v108, 1.0, v109
	v_rcp_f32_e32 v108, v108
	v_mad_i64_i32 v[156:157], s[38:39], v154, s50, v[144:145]
	v_lshlrev_b64 v[146:147], 1, v[146:147]
	v_lshl_add_u64 v[156:157], v[156:157], 0, v[146:147]
	v_add_f32_e32 v109, 1.0, v114
	global_store_dwordx4 v[156:157], v[116:119], off sc0 sc1 nt
	v_rcp_f32_e32 v109, v109
	v_cvt_pk_bf16_f32 v100, v100, v101
	v_mul_f32_e32 v101, v110, v108
	v_mul_f32_e32 v108, 0xbfb8aa3b, v104
	v_exp_f32_e32 v108, v108
	v_mul_f32_e32 v101, v101, v102
	v_mul_f32_e32 v102, v111, v109
	v_mul_f32_e32 v109, 0xbfb8aa3b, v105
	v_exp_f32_e32 v109, v109
	v_mul_f32_e32 v102, v102, v103
	v_add_f32_e32 v103, 1.0, v108
	v_rcp_f32_e32 v103, v103
	v_add_f32_e32 v108, 1.0, v109
	v_rcp_f32_e32 v108, v108
	v_cvt_pk_bf16_f32 v101, v101, v102
	v_mul_f32_e32 v102, v104, v103
	v_mul_f32_e32 v103, 0xbfb8aa3b, v106
	v_exp_f32_e32 v103, v103
	v_mul_f32_e32 v104, 0xbfb8aa3b, v107
	v_exp_f32_e32 v104, v104
	v_mul_f32_e32 v96, v102, v96
	v_mul_f32_e32 v102, v105, v108
	v_mul_f32_e32 v97, v102, v97
	v_add_f32_e32 v102, 1.0, v103
	v_rcp_f32_e32 v103, v102
	v_add_f32_e32 v102, 1.0, v104
	v_rcp_f32_e32 v104, v102
	v_cvt_pk_bf16_f32 v102, v96, v97
	v_mul_f32_e32 v96, v106, v103
	v_mul_f32_e32 v96, v96, v98
	v_mul_f32_e32 v97, v107, v104
	v_mul_f32_e32 v97, v97, v99
	v_cvt_pk_bf16_f32 v103, v96, v97
	v_mul_f32_e32 v97, 0xbfb8aa3b, v92
	v_exp_f32_e32 v98, v97
	v_mul_f32_e32 v97, 0xbfb8aa3b, v93
	v_exp_f32_e32 v99, v97
	v_or_b32_e32 v112, 16, v154
	v_add_f32_e32 v98, 1.0, v98
	v_rcp_f32_e32 v98, v98
	v_add_f32_e32 v99, 1.0, v99
	v_rcp_f32_e32 v99, v99
	v_mad_i64_i32 v[112:113], s[38:39], v112, s50, v[144:145]
	v_mul_f32_e32 v92, v92, v98
	v_mul_f32_e32 v84, v92, v84
	v_mul_f32_e32 v92, v93, v99
	v_mul_f32_e32 v93, 0xbfb8aa3b, v94
	v_exp_f32_e32 v93, v93
	v_mul_f32_e32 v98, 0xbfb8aa3b, v95
	v_exp_f32_e32 v98, v98
	v_mul_f32_e32 v85, v92, v85
	v_add_f32_e32 v92, 1.0, v93
	v_rcp_f32_e32 v92, v92
	v_lshl_add_u64 v[112:113], v[112:113], 0, v[146:147]
	v_add_f32_e32 v93, 1.0, v98
	global_store_dwordx4 v[112:113], v[100:103], off sc0 sc1 nt
	v_rcp_f32_e32 v93, v93
	v_cvt_pk_bf16_f32 v84, v84, v85
	v_mul_f32_e32 v85, v94, v92
	v_mul_f32_e32 v92, 0xbfb8aa3b, v88
	v_exp_f32_e32 v92, v92
	v_mul_f32_e32 v85, v85, v86
	v_mul_f32_e32 v86, v95, v93
	v_mul_f32_e32 v93, 0xbfb8aa3b, v89
	v_exp_f32_e32 v93, v93
	v_mul_f32_e32 v86, v86, v87
	v_add_f32_e32 v87, 1.0, v92
	v_rcp_f32_e32 v87, v87
	v_add_f32_e32 v92, 1.0, v93
	v_rcp_f32_e32 v92, v92
	v_cvt_pk_bf16_f32 v85, v85, v86
	v_mul_f32_e32 v86, v88, v87
	v_mul_f32_e32 v87, 0xbfb8aa3b, v90
	v_exp_f32_e32 v87, v87
	v_mul_f32_e32 v88, 0xbfb8aa3b, v91
	v_exp_f32_e32 v88, v88
	v_mul_f32_e32 v80, v86, v80
	v_mul_f32_e32 v86, v89, v92
	v_mul_f32_e32 v81, v86, v81
	v_add_f32_e32 v86, 1.0, v87
	v_rcp_f32_e32 v87, v86
	v_add_f32_e32 v86, 1.0, v88
	v_rcp_f32_e32 v88, v86
	v_cvt_pk_bf16_f32 v86, v80, v81
	v_mul_f32_e32 v80, v90, v87
	v_mul_f32_e32 v80, v80, v82
	v_mul_f32_e32 v81, v91, v88
	v_mul_f32_e32 v81, v81, v83
	v_cvt_pk_bf16_f32 v87, v80, v81
	v_mul_f32_e32 v81, 0xbfb8aa3b, v76
; __device__ __forceinline__ unsigned cvt_pk_bf16(float lo, float hi) { unsigned r; asm volatile("v_cvt_pk_bf16_f32 %0, %1, %2" : "=v"(r) : "v"(lo), "v"(hi)); return r; }
; __device__ __forceinline__ float sigm(float x) { return __builtin_amdgcn_rcpf(1.0f + __builtin_amdgcn_exp2f(-1.4426950408889634f * x)); }
;     __device__ __forceinline__ void operator()(const f32x4 (&acc)[2][2][4][2], const Unit& u, int wr, int wc, int fr, int fq) const {
;         const int row0 = u.pm * BM + wr * 64 + fr, col0 = u.pn * 128 + wc * 32 + 8 * fq;
; #pragma unroll
;         for (int ai = 0; ai < 2; ++ai)
; #pragma unroll
;             for (int m = 0; m < 4; ++m) { bf16_t* rowp = out + (size_t)(row0 + ai * HALF + m * 16) * 2816 + col0;
;                 const f32x4 g0 = acc[ai][0][m][0], g1 = acc[ai][0][m][1], u0 = acc[ai][1][m][0], u1 = acc[ai][1][m][1];
;                 u32x4 w;
;                 w.x = cvt_pk_bf16(g0[0] * sigm(g0[0]) * u0[0], g0[1] * sigm(g0[1]) * u0[1]);
;                 w.y = cvt_pk_bf16(g0[2] * sigm(g0[2]) * u0[2], g0[3] * sigm(g0[3]) * u0[3]);
;                 w.z = cvt_pk_bf16(g1[0] * sigm(g1[0]) * u1[0], g1[1] * sigm(g1[1]) * u1[1]);
;                 w.w = cvt_pk_bf16(g1[2] * sigm(g1[2]) * u1[2], g1[3] * sigm(g1[3]) * u1[3]);
;                 __builtin_nontemporal_store(w, (u32x4*)rowp); }
	v_exp_f32_e32 v82, v81
	v_mul_f32_e32 v81, 0xbfb8aa3b, v77
	v_exp_f32_e32 v83, v81
	v_or_b32_e32 v96, 32, v154
	v_add_f32_e32 v82, 1.0, v82
	v_rcp_f32_e32 v82, v82
	v_add_f32_e32 v83, 1.0, v83
	v_rcp_f32_e32 v83, v83
	v_mad_i64_i32 v[96:97], s[38:39], v96, s50, v[144:145]
	v_mul_f32_e32 v76, v76, v82
	v_mul_f32_e32 v68, v76, v68
	v_mul_f32_e32 v76, v77, v83
	v_mul_f32_e32 v77, 0xbfb8aa3b, v78
	v_exp_f32_e32 v77, v77
	v_mul_f32_e32 v82, 0xbfb8aa3b, v79
	v_exp_f32_e32 v82, v82
	v_mul_f32_e32 v69, v76, v69
	v_add_f32_e32 v76, 1.0, v77
	v_rcp_f32_e32 v76, v76
	v_lshl_add_u64 v[96:97], v[96:97], 0, v[146:147]
	v_add_f32_e32 v77, 1.0, v82
	global_store_dwordx4 v[96:97], v[84:87], off sc0 sc1 nt
	v_rcp_f32_e32 v77, v77
	v_cvt_pk_bf16_f32 v68, v68, v69
	v_mul_f32_e32 v69, v78, v76
	v_mul_f32_e32 v76, 0xbfb8aa3b, v72
	v_exp_f32_e32 v76, v76
	v_mul_f32_e32 v69, v69, v70
	v_mul_f32_e32 v70, v79, v77
	v_mul_f32_e32 v77, 0xbfb8aa3b, v73
	v_exp_f32_e32 v77, v77
	v_mul_f32_e32 v70, v70, v71
	v_add_f32_e32 v71, 1.0, v76
	v_rcp_f32_e32 v71, v71
	v_add_f32_e32 v76, 1.0, v77
	v_rcp_f32_e32 v76, v76
	v_cvt_pk_bf16_f32 v69, v69, v70
	v_mul_f32_e32 v70, v72, v71
	v_mul_f32_e32 v71, 0xbfb8aa3b, v74
	v_exp_f32_e32 v71, v71
	v_mul_f32_e32 v72, 0xbfb8aa3b, v75
	v_exp_f32_e32 v72, v72
	v_mul_f32_e32 v64, v70, v64
	v_mul_f32_e32 v70, v73, v76
	v_mul_f32_e32 v65, v70, v65
	v_add_f32_e32 v70, 1.0, v71
	v_rcp_f32_e32 v71, v70
	v_add_f32_e32 v70, 1.0, v72
	v_rcp_f32_e32 v72, v70
	v_cvt_pk_bf16_f32 v70, v64, v65
	v_mul_f32_e32 v64, v74, v71
	v_mul_f32_e32 v64, v64, v66
	v_mul_f32_e32 v65, v75, v72
	v_mul_f32_e32 v65, v65, v67
	v_cvt_pk_bf16_f32 v71, v64, v65
	v_mul_f32_e32 v65, 0xbfb8aa3b, v60
	v_exp_f32_e32 v66, v65
	v_mul_f32_e32 v65, 0xbfb8aa3b, v61
	v_exp_f32_e32 v67, v65
	v_or_b32_e32 v80, 48, v154
	v_add_f32_e32 v66, 1.0, v66
	v_rcp_f32_e32 v66, v66
	v_add_f32_e32 v67, 1.0, v67
	v_rcp_f32_e32 v67, v67
	v_mad_i64_i32 v[80:81], s[38:39], v80, s50, v[144:145]
	v_mul_f32_e32 v60, v60, v66
	v_mul_f32_e32 v52, v60, v52
	v_mul_f32_e32 v60, v61, v67
	v_mul_f32_e32 v61, 0xbfb8aa3b, v62
	v_exp_f32_e32 v61, v61
	v_mul_f32_e32 v66, 0xbfb8aa3b, v63
	v_exp_f32_e32 v66, v66
	v_mul_f32_e32 v53, v60, v53
	v_add_f32_e32 v60, 1.0, v61
	v_rcp_f32_e32 v60, v60
	v_lshl_add_u64 v[80:81], v[80:81], 0, v[146:147]
	v_add_f32_e32 v61, 1.0, v66
	global_store_dwordx4 v[80:81], v[68:71], off sc0 sc1 nt
	v_rcp_f32_e32 v61, v61
	v_cvt_pk_bf16_f32 v52, v52, v53
	v_mul_f32_e32 v53, v62, v60
	v_mul_f32_e32 v60, 0xbfb8aa3b, v56
	v_exp_f32_e32 v60, v60
	v_mul_f32_e32 v53, v53, v54
	v_mul_f32_e32 v54, v63, v61
	v_mul_f32_e32 v61, 0xbfb8aa3b, v57
	v_exp_f32_e32 v61, v61
	v_mul_f32_e32 v54, v54, v55
	v_add_f32_e32 v55, 1.0, v60
	v_rcp_f32_e32 v55, v55
	v_add_f32_e32 v60, 1.0, v61
	v_rcp_f32_e32 v60, v60
	v_cvt_pk_bf16_f32 v53, v53, v54
	v_mul_f32_e32 v54, v56, v55
	v_mul_f32_e32 v55, 0xbfb8aa3b, v58
	v_exp_f32_e32 v55, v55
	v_mul_f32_e32 v56, 0xbfb8aa3b, v59
	v_exp_f32_e32 v56, v56
	v_mul_f32_e32 v48, v54, v48
	v_mul_f32_e32 v54, v57, v60
	v_mul_f32_e32 v49, v54, v49
	v_add_f32_e32 v54, 1.0, v55
	v_rcp_f32_e32 v55, v54
	v_add_f32_e32 v54, 1.0, v56
	v_rcp_f32_e32 v56, v54
	v_cvt_pk_bf16_f32 v54, v48, v49
	v_mul_f32_e32 v48, v58, v55
	v_mul_f32_e32 v48, v48, v50
	v_mul_f32_e32 v49, v59, v56
	v_mul_f32_e32 v49, v49, v51
	v_cvt_pk_bf16_f32 v55, v48, v49
	v_mul_f32_e32 v49, 0xbfb8aa3b, v44
	v_exp_f32_e32 v50, v49
	v_mul_f32_e32 v49, 0xbfb8aa3b, v45
	v_exp_f32_e32 v51, v49
	v_add_u32_e32 v64, 0x80, v154
	v_add_f32_e32 v50, 1.0, v50
	v_rcp_f32_e32 v50, v50
	v_add_f32_e32 v51, 1.0, v51
	v_rcp_f32_e32 v51, v51
	v_mad_i64_i32 v[64:65], s[38:39], v64, s50, v[144:145]
	v_mul_f32_e32 v44, v44, v50
	v_mul_f32_e32 v36, v44, v36
	v_mul_f32_e32 v44, v45, v51
	v_mul_f32_e32 v45, 0xbfb8aa3b, v46
	v_exp_f32_e32 v45, v45
	v_mul_f32_e32 v50, 0xbfb8aa3b, v47
	v_exp_f32_e32 v50, v50
	v_mul_f32_e32 v37, v44, v37
	v_add_f32_e32 v44, 1.0, v45
	v_rcp_f32_e32 v44, v44
	v_lshl_add_u64 v[64:65], v[64:65], 0, v[146:147]
	v_add_f32_e32 v45, 1.0, v50
	global_store_dwordx4 v[64:65], v[52:55], off sc0 sc1 nt
	v_rcp_f32_e32 v45, v45
	v_cvt_pk_bf16_f32 v36, v36, v37
	v_mul_f32_e32 v37, v46, v44
	v_mul_f32_e32 v44, 0xbfb8aa3b, v40
	v_exp_f32_e32 v44, v44
	v_mul_f32_e32 v37, v37, v38
	v_mul_f32_e32 v38, v47, v45
	v_mul_f32_e32 v45, 0xbfb8aa3b, v41
	v_exp_f32_e32 v45, v45
; __device__ __forceinline__ unsigned cvt_pk_bf16(float lo, float hi) { unsigned r; asm volatile("v_cvt_pk_bf16_f32 %0, %1, %2" : "=v"(r) : "v"(lo), "v"(hi)); return r; }
; __device__ __forceinline__ float sigm(float x) { return __builtin_amdgcn_rcpf(1.0f + __builtin_amdgcn_exp2f(-1.4426950408889634f * x)); }
;     __device__ __forceinline__ void operator()(const f32x4 (&acc)[2][2][4][2], const Unit& u, int wr, int wc, int fr, int fq) const {
;         const int row0 = u.pm * BM + wr * 64 + fr, col0 = u.pn * 128 + wc * 32 + 8 * fq;
; #pragma unroll
;         for (int ai = 0; ai < 2; ++ai)
; #pragma unroll
;             for (int m = 0; m < 4; ++m) { bf16_t* rowp = out + (size_t)(row0 + ai * HALF + m * 16) * 2816 + col0;
;                 const f32x4 g0 = acc[ai][0][m][0], g1 = acc[ai][0][m][1], u0 = acc[ai][1][m][0], u1 = acc[ai][1][m][1];
;                 u32x4 w;
;                 w.x = cvt_pk_bf16(g0[0] * sigm(g0[0]) * u0[0], g0[1] * sigm(g0[1]) * u0[1]);
;                 w.y = cvt_pk_bf16(g0[2] * sigm(g0[2]) * u0[2], g0[3] * sigm(g0[3]) * u0[3]);
;                 w.z = cvt_pk_bf16(g1[0] * sigm(g1[0]) * u1[0], g1[1] * sigm(g1[1]) * u1[1]);
;                 w.w = cvt_pk_bf16(g1[2] * sigm(g1[2]) * u1[2], g1[3] * sigm(g1[3]) * u1[3]);
;                 __builtin_nontemporal_store(w, (u32x4*)rowp); }
	v_mul_f32_e32 v38, v38, v39
	v_add_f32_e32 v39, 1.0, v44
	v_rcp_f32_e32 v39, v39
	v_add_f32_e32 v44, 1.0, v45
	v_rcp_f32_e32 v44, v44
	v_cvt_pk_bf16_f32 v37, v37, v38
	v_mul_f32_e32 v38, v40, v39
	v_mul_f32_e32 v39, 0xbfb8aa3b, v42
	v_exp_f32_e32 v39, v39
	v_mul_f32_e32 v40, 0xbfb8aa3b, v43
	v_exp_f32_e32 v40, v40
	v_mul_f32_e32 v32, v38, v32
	v_mul_f32_e32 v38, v41, v44
	v_mul_f32_e32 v33, v38, v33
	v_add_f32_e32 v38, 1.0, v39
	v_rcp_f32_e32 v39, v38
	v_add_f32_e32 v38, 1.0, v40
	v_rcp_f32_e32 v40, v38
	v_cvt_pk_bf16_f32 v38, v32, v33
	v_mul_f32_e32 v32, v42, v39
	v_mul_f32_e32 v32, v32, v34
	v_mul_f32_e32 v33, v43, v40
	v_mul_f32_e32 v33, v33, v35
	v_cvt_pk_bf16_f32 v39, v32, v33
	v_mul_f32_e32 v33, 0xbfb8aa3b, v28
	v_exp_f32_e32 v34, v33
	v_mul_f32_e32 v33, 0xbfb8aa3b, v29
	v_exp_f32_e32 v35, v33
	v_add_u32_e32 v48, 0x90, v154
	v_add_f32_e32 v34, 1.0, v34
	v_rcp_f32_e32 v34, v34
	v_add_f32_e32 v35, 1.0, v35
	v_rcp_f32_e32 v35, v35
	v_mad_i64_i32 v[48:49], s[38:39], v48, s50, v[144:145]
	v_mul_f32_e32 v28, v28, v34
	v_mul_f32_e32 v20, v28, v20
	v_mul_f32_e32 v28, v29, v35
	v_mul_f32_e32 v29, 0xbfb8aa3b, v30
	v_exp_f32_e32 v29, v29
	v_mul_f32_e32 v34, 0xbfb8aa3b, v31
	v_exp_f32_e32 v34, v34
	v_mul_f32_e32 v21, v28, v21
	v_add_f32_e32 v28, 1.0, v29
	v_rcp_f32_e32 v28, v28
	v_lshl_add_u64 v[48:49], v[48:49], 0, v[146:147]
	v_add_f32_e32 v29, 1.0, v34
	global_store_dwordx4 v[48:49], v[36:39], off sc0 sc1 nt
	v_rcp_f32_e32 v29, v29
	v_cvt_pk_bf16_f32 v20, v20, v21
	v_mul_f32_e32 v21, v30, v28
	v_mul_f32_e32 v28, 0xbfb8aa3b, v24
	v_exp_f32_e32 v28, v28
	v_mul_f32_e32 v21, v21, v22
	v_mul_f32_e32 v22, v31, v29
	v_mul_f32_e32 v29, 0xbfb8aa3b, v25
	v_exp_f32_e32 v29, v29
	v_mul_f32_e32 v22, v22, v23
	v_add_f32_e32 v23, 1.0, v28
	v_rcp_f32_e32 v23, v23
	v_add_f32_e32 v28, 1.0, v29
	v_rcp_f32_e32 v28, v28
	v_cvt_pk_bf16_f32 v21, v21, v22
	v_mul_f32_e32 v22, v24, v23
	v_mul_f32_e32 v23, 0xbfb8aa3b, v26
	v_exp_f32_e32 v23, v23
	v_mul_f32_e32 v24, 0xbfb8aa3b, v27
	v_exp_f32_e32 v24, v24
	v_mul_f32_e32 v16, v22, v16
	v_mul_f32_e32 v22, v25, v28
	v_mul_f32_e32 v17, v22, v17
	v_add_f32_e32 v22, 1.0, v23
	v_rcp_f32_e32 v23, v22
	v_add_f32_e32 v22, 1.0, v24
	v_rcp_f32_e32 v24, v22
	v_cvt_pk_bf16_f32 v22, v16, v17
	v_mul_f32_e32 v16, v26, v23
	v_mul_f32_e32 v16, v16, v18
	v_mul_f32_e32 v17, v27, v24
	v_mul_f32_e32 v17, v17, v19
	v_cvt_pk_bf16_f32 v23, v16, v17
	v_mul_f32_e32 v17, 0xbfb8aa3b, v12
	v_exp_f32_e32 v18, v17
	v_mul_f32_e32 v17, 0xbfb8aa3b, v13
	v_exp_f32_e32 v19, v17
	v_add_u32_e32 v32, 0xa0, v154
	v_add_f32_e32 v18, 1.0, v18
	v_rcp_f32_e32 v18, v18
	v_add_f32_e32 v19, 1.0, v19
	v_rcp_f32_e32 v19, v19
	v_mad_i64_i32 v[32:33], s[38:39], v32, s50, v[144:145]
	v_mul_f32_e32 v12, v12, v18
	v_mul_f32_e32 v4, v12, v4
	v_mul_f32_e32 v12, v13, v19
	v_mul_f32_e32 v13, 0xbfb8aa3b, v14
	v_exp_f32_e32 v13, v13
	v_mul_f32_e32 v18, 0xbfb8aa3b, v15
	v_exp_f32_e32 v18, v18
	v_mul_f32_e32 v5, v12, v5
	v_add_f32_e32 v12, 1.0, v13
	v_rcp_f32_e32 v12, v12
	v_lshl_add_u64 v[32:33], v[32:33], 0, v[146:147]
	v_add_f32_e32 v13, 1.0, v18
	global_store_dwordx4 v[32:33], v[20:23], off sc0 sc1 nt
	v_rcp_f32_e32 v13, v13
	v_cvt_pk_bf16_f32 v4, v4, v5
	v_mul_f32_e32 v5, v14, v12
	v_mul_f32_e32 v12, 0xbfb8aa3b, v8
	v_exp_f32_e32 v12, v12
	v_mul_f32_e32 v5, v5, v6
	v_mul_f32_e32 v6, v15, v13
	v_mul_f32_e32 v13, 0xbfb8aa3b, v9
	v_exp_f32_e32 v13, v13
	v_mul_f32_e32 v6, v6, v7
	v_add_f32_e32 v7, 1.0, v12
	v_rcp_f32_e32 v7, v7
	v_add_f32_e32 v12, 1.0, v13
	v_rcp_f32_e32 v12, v12
	v_cvt_pk_bf16_f32 v5, v5, v6
	v_mul_f32_e32 v6, v8, v7
	v_mul_f32_e32 v7, 0xbfb8aa3b, v10
	v_exp_f32_e32 v7, v7
	v_mul_f32_e32 v8, 0xbfb8aa3b, v11
	v_exp_f32_e32 v8, v8
	v_mul_f32_e32 v0, v6, v0
	v_mul_f32_e32 v6, v9, v12
	v_mul_f32_e32 v1, v6, v1
	v_add_f32_e32 v6, 1.0, v7
	v_rcp_f32_e32 v7, v6
	v_add_f32_e32 v6, 1.0, v8
	v_rcp_f32_e32 v8, v6
	v_add_u32_e32 v16, 0xb0, v154
	v_mad_i64_i32 v[16:17], s[38:39], v16, s50, v[144:145]
	v_lshl_add_u64 v[16:17], v[16:17], 0, v[146:147]
	v_cvt_pk_bf16_f32 v6, v0, v1
	v_mul_f32_e32 v0, v10, v7
	v_mul_f32_e32 v1, v11, v8
	s_andn2_b64 vcc, exec, s[2:3]
	s_mov_b64 s[2:3], -1
	v_mul_f32_e32 v0, v0, v2
	v_mul_f32_e32 v1, v1, v3
	v_cvt_pk_bf16_f32 v7, v0, v1
	global_store_dwordx4 v[16:17], v[4:7], off sc0 sc1 nt
	s_cbranch_vccnz .LBB0_601
	s_andn2_b64 vcc, exec, s[0:1]
	s_cbranch_vccnz .LBB0_600
	s_barrier
	s_branch .LBB0_600
